# dn_prep stage 2 epilogue: the 31 per-element gc/beta LDS reads issued together up front instead of one round trip per element
# speedup vs baseline: 1.0021x; 1.0021x over previous
; #define LAS __attribute__((address_space(3)))
; __device__ __forceinline__ unsigned pk2(float lo, float hi) { const f32x2_t v = {lo, hi}; const bf16x2_t b = __builtin_convertvector(v, bf16x2_t); return __builtin_bit_cast(unsigned, b); }
; __device__ __forceinline__ void dn_prep_item(const Args& a, LAS unsigned char* lds, int item, int tid, int wave, int lane, int& cwh, int next_item) {
;     ...
;       const int j = 32 * tj + rr; const float gj = gcs[j];
; #pragma unroll
;       for (int r = 0; r < 16; ++r) { const int i = 32 * ti + (r & 3) + 8 * (r >> 2) + 4 * hh;
;           const float dec = __expf(fminf(gcs[i] - gj, 0.f));
;           if (isq) { const float v = (i >= j) ? acc[r] * dec : 0.f; *(LAS unsigned short*)(lds + L_AT + i * AS_ + 2 * j) = (unsigned short)(pk2(v, 0.f) & 0xffffu); }
;           else { Lm[i * 68 + j] = (i > j) ? -(betas[i] * acc[r] * dec) : 0.f; } }
.LBB0_772:
	ds_read_b32 v16, v152
	ds_read_b32 v17, v154
	ds_read_b32 v88, v155
	ds_read_b32 v89, v157
	ds_read_b32 v90, v158
	ds_read_b32 v91, v159
	ds_read_b32 v92, v160
	ds_read_b32 v93, v161
	ds_read_b32 v94, v162
	ds_read_b32 v95, v163
	ds_read_b32 v96, v164
	ds_read_b32 v97, v165
	ds_read_b32 v98, v166
	ds_read_b32 v99, v167
	ds_read_b32 v100, v168
	ds_read_b32 v101, v169
	ds_read_b32 v102, v170
	ds_read_b32 v103, v171
	ds_read_b32 v104, v172
	ds_read_b32 v105, v173
	ds_read_b32 v106, v174
	ds_read_b32 v107, v175
	ds_read_b32 v108, v176
	ds_read_b32 v109, v177
	ds_read_b32 v110, v178
	ds_read_b32 v111, v179
	ds_read_b32 v112, v180
	ds_read_b32 v113, v181
	ds_read_b32 v114, v182
	ds_read_b32 v115, v183
	ds_read_b32 v116, v184
	ds_read_b32 v117, v185
	ds_read_b32 v118, v186
	v_cndmask_b32_e64 v18, 0, 1, s[20:21]
	v_cmp_ne_u32_e64 s[86:87], 1, v18
	s_andn2_b64 vcc, exec, s[20:21]
	s_mov_b64 s[22:23], -1
	s_waitcnt lgkmcnt(0)
	v_sub_f32_e32 v17, v17, v16
	v_min_f32_e32 v17, 0, v17
	v_mul_f32_e32 v17, 0x3fb8aa3b, v17
	v_exp_f32_e32 v17, v17
	s_cbranch_vccnz .LBB0_774
	v_mul_f32_e32 v18, v0, v17
	v_readlane_b32 s22, v244, 23
	v_cvt_pk_bf16_f32 v18, v18, s0
	v_readlane_b32 s23, v244, 24
	s_nop 1
	v_cndmask_b32_e64 v18, v18, 0, s[22:23]
	s_mov_b64 s[22:23], 0
	ds_write_b16 v233, v18 offset:52224
.LBB0_774:
	s_andn2_b64 vcc, exec, s[22:23]
	s_cbranch_vccnz .LBB0_778
	v_mov_b32_e32 v18, 0
	s_mov_b64 s[22:23], exec
	v_readlane_b32 s42, v244, 27
	v_readlane_b32 s43, v244, 28
	s_and_b64 s[42:43], s[22:23], s[42:43]
	s_mov_b64 exec, s[42:43]
	s_cbranch_execz .LBB0_777
	v_mov_b32_e32 v18, v88
	s_waitcnt lgkmcnt(0)
	v_mul_f32_e32 v0, v0, v18
	v_mul_f32_e64 v18, v0, -v17

; #define LAS __attribute__((address_space(3)))
; __device__ __forceinline__ unsigned pk2(float lo, float hi) { const f32x2_t v = {lo, hi}; const bf16x2_t b = __builtin_convertvector(v, bf16x2_t); return __builtin_bit_cast(unsigned, b); }
; __device__ __forceinline__ void dn_prep_item(const Args& a, LAS unsigned char* lds, int item, int tid, int wave, int lane, int& cwh, int next_item) {
;     ...
;       for (int r = 0; r < 16; ++r) { const int i = 32 * ti + (r & 3) + 8 * (r >> 2) + 4 * hh;
;           const float dec = __expf(fminf(gcs[i] - gj, 0.f));
;           if (isq) { const float v = (i >= j) ? acc[r] * dec : 0.f; *(LAS unsigned short*)(lds + L_AT + i * AS_ + 2 * j) = (unsigned short)(pk2(v, 0.f) & 0xffffu); }
;           else { Lm[i * 68 + j] = (i > j) ? -(betas[i] * acc[r] * dec) : 0.f; } }
.LBB0_778:
	v_mov_b32_e32 v0, v89
	s_and_b64 vcc, exec, s[86:87]
	s_mov_b64 s[22:23], -1
	s_waitcnt lgkmcnt(0)
	v_sub_f32_e32 v0, v0, v16
	v_min_f32_e32 v0, 0, v0
	v_mul_f32_e32 v0, 0x3fb8aa3b, v0
	v_exp_f32_e32 v0, v0
	s_cbranch_vccnz .LBB0_780
	v_mul_f32_e32 v17, v1, v0
	v_readlane_b32 s22, v244, 29
	v_cvt_pk_bf16_f32 v17, v17, s0
	v_readlane_b32 s23, v244, 30
	s_nop 1
	v_cndmask_b32_e64 v17, v17, 0, s[22:23]
	s_mov_b64 s[22:23], 0
	ds_write_b16 v233, v17 offset:52368
.LBB0_780:
	s_andn2_b64 vcc, exec, s[22:23]
	s_cbranch_vccnz .LBB0_784
	v_mov_b32_e32 v17, 0
	s_mov_b64 s[22:23], exec
	v_readlane_b32 s42, v244, 25
	v_readlane_b32 s43, v244, 26
	s_and_b64 s[42:43], s[22:23], s[42:43]
	s_mov_b64 exec, s[42:43]
	s_cbranch_execz .LBB0_783
	v_mov_b32_e32 v17, v90
	s_waitcnt lgkmcnt(0)
	v_mul_f32_e32 v1, v1, v17
	v_mul_f32_e64 v17, v1, -v0

; #define LAS __attribute__((address_space(3)))
; __device__ __forceinline__ unsigned pk2(float lo, float hi) { const f32x2_t v = {lo, hi}; const bf16x2_t b = __builtin_convertvector(v, bf16x2_t); return __builtin_bit_cast(unsigned, b); }
; __device__ __forceinline__ void dn_prep_item(const Args& a, LAS unsigned char* lds, int item, int tid, int wave, int lane, int& cwh, int next_item) {
;     ...
;       for (int r = 0; r < 16; ++r) { const int i = 32 * ti + (r & 3) + 8 * (r >> 2) + 4 * hh;
;           const float dec = __expf(fminf(gcs[i] - gj, 0.f));
;           if (isq) { const float v = (i >= j) ? acc[r] * dec : 0.f; *(LAS unsigned short*)(lds + L_AT + i * AS_ + 2 * j) = (unsigned short)(pk2(v, 0.f) & 0xffffu); }
;           else { Lm[i * 68 + j] = (i > j) ? -(betas[i] * acc[r] * dec) : 0.f; } }
.LBB0_784:
	v_mov_b32_e32 v0, v91
	s_and_b64 vcc, exec, s[86:87]
	s_mov_b64 s[22:23], -1
	s_waitcnt lgkmcnt(0)
	v_sub_f32_e32 v0, v0, v16
	v_min_f32_e32 v0, 0, v0
	v_mul_f32_e32 v0, 0x3fb8aa3b, v0
	v_exp_f32_e32 v0, v0
	s_cbranch_vccnz .LBB0_786
	v_mul_f32_e32 v1, v2, v0
	v_readlane_b32 s22, v244, 31
	v_cvt_pk_bf16_f32 v1, v1, s0
	v_readlane_b32 s23, v244, 32
	s_nop 1
	v_cndmask_b32_e64 v1, v1, 0, s[22:23]
	s_mov_b64 s[22:23], 0
	ds_write_b16 v233, v1 offset:52512
.LBB0_786:
	s_andn2_b64 vcc, exec, s[22:23]
	s_cbranch_vccnz .LBB0_790
	v_mov_b32_e32 v1, 0
	s_mov_b64 s[22:23], exec
	v_readlane_b32 s42, v244, 33
	v_readlane_b32 s43, v244, 34
	s_and_b64 s[42:43], s[22:23], s[42:43]
	s_mov_b64 exec, s[42:43]
	s_cbranch_execz .LBB0_789
	v_mov_b32_e32 v1, v92
	s_waitcnt lgkmcnt(0)
	v_mul_f32_e32 v1, v2, v1
	v_mul_f32_e64 v1, v1, -v0

; #define LAS __attribute__((address_space(3)))
; __device__ __forceinline__ unsigned pk2(float lo, float hi) { const f32x2_t v = {lo, hi}; const bf16x2_t b = __builtin_convertvector(v, bf16x2_t); return __builtin_bit_cast(unsigned, b); }
; __device__ __forceinline__ void dn_prep_item(const Args& a, LAS unsigned char* lds, int item, int tid, int wave, int lane, int& cwh, int next_item) {
;     ...
;       for (int r = 0; r < 16; ++r) { const int i = 32 * ti + (r & 3) + 8 * (r >> 2) + 4 * hh;
;           const float dec = __expf(fminf(gcs[i] - gj, 0.f));
;           if (isq) { const float v = (i >= j) ? acc[r] * dec : 0.f; *(LAS unsigned short*)(lds + L_AT + i * AS_ + 2 * j) = (unsigned short)(pk2(v, 0.f) & 0xffffu); }
;           else { Lm[i * 68 + j] = (i > j) ? -(betas[i] * acc[r] * dec) : 0.f; } }
.LBB0_790:
	v_mov_b32_e32 v0, v93
	s_and_b64 vcc, exec, s[86:87]
	s_mov_b64 s[22:23], -1
	s_waitcnt lgkmcnt(0)
	v_sub_f32_e32 v0, v0, v16
	v_min_f32_e32 v0, 0, v0
	v_mul_f32_e32 v0, 0x3fb8aa3b, v0
	v_exp_f32_e32 v0, v0
	s_cbranch_vccnz .LBB0_792
	v_mul_f32_e32 v1, v3, v0
	v_readlane_b32 s22, v244, 35
	v_cvt_pk_bf16_f32 v1, v1, s0
	v_readlane_b32 s23, v244, 36
	s_nop 1
	v_cndmask_b32_e64 v1, v1, 0, s[22:23]
	s_mov_b64 s[22:23], 0
	ds_write_b16 v233, v1 offset:52656
.LBB0_792:
	s_andn2_b64 vcc, exec, s[22:23]
	s_cbranch_vccnz .LBB0_796
	v_mov_b32_e32 v1, 0
	s_mov_b64 s[22:23], exec
	v_readlane_b32 s42, v244, 37
	v_readlane_b32 s43, v244, 38
	s_and_b64 s[42:43], s[22:23], s[42:43]
	s_mov_b64 exec, s[42:43]
	s_cbranch_execz .LBB0_795
	v_mov_b32_e32 v1, v94
	s_waitcnt lgkmcnt(0)
	v_mul_f32_e32 v1, v3, v1
	v_mul_f32_e64 v1, v1, -v0

; #define LAS __attribute__((address_space(3)))
; __device__ __forceinline__ unsigned pk2(float lo, float hi) { const f32x2_t v = {lo, hi}; const bf16x2_t b = __builtin_convertvector(v, bf16x2_t); return __builtin_bit_cast(unsigned, b); }
; __device__ __forceinline__ void dn_prep_item(const Args& a, LAS unsigned char* lds, int item, int tid, int wave, int lane, int& cwh, int next_item) {
;     ...
;       for (int r = 0; r < 16; ++r) { const int i = 32 * ti + (r & 3) + 8 * (r >> 2) + 4 * hh;
;           const float dec = __expf(fminf(gcs[i] - gj, 0.f));
;           if (isq) { const float v = (i >= j) ? acc[r] * dec : 0.f; *(LAS unsigned short*)(lds + L_AT + i * AS_ + 2 * j) = (unsigned short)(pk2(v, 0.f) & 0xffffu); }
;           else { Lm[i * 68 + j] = (i > j) ? -(betas[i] * acc[r] * dec) : 0.f; } }
.LBB0_796:
	v_mov_b32_e32 v0, v95
	s_and_b64 vcc, exec, s[86:87]
	s_mov_b64 s[22:23], -1
	s_waitcnt lgkmcnt(0)
	v_sub_f32_e32 v0, v0, v16
	v_min_f32_e32 v0, 0, v0
	v_mul_f32_e32 v0, 0x3fb8aa3b, v0
	v_exp_f32_e32 v0, v0
	s_cbranch_vccnz .LBB0_798
	v_mul_f32_e32 v1, v4, v0
	v_readlane_b32 s22, v244, 39
	v_cvt_pk_bf16_f32 v1, v1, s0
	v_readlane_b32 s23, v244, 40
	s_nop 1
	v_cndmask_b32_e64 v1, v1, 0, s[22:23]
	s_mov_b64 s[22:23], 0
	ds_write_b16 v233, v1 offset:53376
.LBB0_798:
	s_andn2_b64 vcc, exec, s[22:23]
	s_cbranch_vccnz .LBB0_802
	v_mov_b32_e32 v1, 0
	s_mov_b64 s[22:23], exec
	v_readlane_b32 s42, v244, 41
	v_readlane_b32 s43, v244, 42
	s_and_b64 s[42:43], s[22:23], s[42:43]
	s_mov_b64 exec, s[42:43]
	s_cbranch_execz .LBB0_801
	v_mov_b32_e32 v1, v96
	s_waitcnt lgkmcnt(0)
	v_mul_f32_e32 v1, v4, v1
	v_mul_f32_e64 v1, v1, -v0

; #define LAS __attribute__((address_space(3)))
; __device__ __forceinline__ unsigned pk2(float lo, float hi) { const f32x2_t v = {lo, hi}; const bf16x2_t b = __builtin_convertvector(v, bf16x2_t); return __builtin_bit_cast(unsigned, b); }
; __device__ __forceinline__ void dn_prep_item(const Args& a, LAS unsigned char* lds, int item, int tid, int wave, int lane, int& cwh, int next_item) {
;     ...
;       for (int r = 0; r < 16; ++r) { const int i = 32 * ti + (r & 3) + 8 * (r >> 2) + 4 * hh;
;           const float dec = __expf(fminf(gcs[i] - gj, 0.f));
;           if (isq) { const float v = (i >= j) ? acc[r] * dec : 0.f; *(LAS unsigned short*)(lds + L_AT + i * AS_ + 2 * j) = (unsigned short)(pk2(v, 0.f) & 0xffffu); }
;           else { Lm[i * 68 + j] = (i > j) ? -(betas[i] * acc[r] * dec) : 0.f; } }
.LBB0_802:
	v_mov_b32_e32 v0, v97
	s_and_b64 vcc, exec, s[86:87]
	s_mov_b64 s[22:23], -1
	s_waitcnt lgkmcnt(0)
	v_sub_f32_e32 v0, v0, v16
	v_min_f32_e32 v0, 0, v0
	v_mul_f32_e32 v0, 0x3fb8aa3b, v0
	v_exp_f32_e32 v0, v0
	s_cbranch_vccnz .LBB0_804
	v_mul_f32_e32 v1, v5, v0
	v_readlane_b32 s22, v244, 43
	v_cvt_pk_bf16_f32 v1, v1, s0
	v_readlane_b32 s23, v244, 44
	s_nop 1
	v_cndmask_b32_e64 v1, v1, 0, s[22:23]
	s_mov_b64 s[22:23], 0
	ds_write_b16 v233, v1 offset:53520
.LBB0_804:
	s_andn2_b64 vcc, exec, s[22:23]
	s_cbranch_vccnz .LBB0_808
	v_mov_b32_e32 v1, 0
	s_mov_b64 s[22:23], exec
	v_readlane_b32 s42, v244, 45
	v_readlane_b32 s43, v244, 46
	s_and_b64 s[42:43], s[22:23], s[42:43]
	s_mov_b64 exec, s[42:43]
	s_cbranch_execz .LBB0_807
	v_mov_b32_e32 v1, v98
	s_waitcnt lgkmcnt(0)
	v_mul_f32_e32 v1, v5, v1
	v_mul_f32_e64 v1, v1, -v0

; #define LAS __attribute__((address_space(3)))
; __device__ __forceinline__ unsigned pk2(float lo, float hi) { const f32x2_t v = {lo, hi}; const bf16x2_t b = __builtin_convertvector(v, bf16x2_t); return __builtin_bit_cast(unsigned, b); }
; __device__ __forceinline__ void dn_prep_item(const Args& a, LAS unsigned char* lds, int item, int tid, int wave, int lane, int& cwh, int next_item) {
;     ...
;       for (int r = 0; r < 16; ++r) { const int i = 32 * ti + (r & 3) + 8 * (r >> 2) + 4 * hh;
;           const float dec = __expf(fminf(gcs[i] - gj, 0.f));
;           if (isq) { const float v = (i >= j) ? acc[r] * dec : 0.f; *(LAS unsigned short*)(lds + L_AT + i * AS_ + 2 * j) = (unsigned short)(pk2(v, 0.f) & 0xffffu); }
;           else { Lm[i * 68 + j] = (i > j) ? -(betas[i] * acc[r] * dec) : 0.f; } }
.LBB0_808:
	v_mov_b32_e32 v0, v99
	s_and_b64 vcc, exec, s[86:87]
	s_mov_b64 s[22:23], -1
	s_waitcnt lgkmcnt(0)
	v_sub_f32_e32 v0, v0, v16
	v_min_f32_e32 v0, 0, v0
	v_mul_f32_e32 v0, 0x3fb8aa3b, v0
	v_exp_f32_e32 v0, v0
	s_cbranch_vccnz .LBB0_810
	v_mul_f32_e32 v1, v6, v0
	v_readlane_b32 s22, v244, 47
	v_cvt_pk_bf16_f32 v1, v1, s0
	v_readlane_b32 s23, v244, 48
	s_nop 1
	v_cndmask_b32_e64 v1, v1, 0, s[22:23]
	s_mov_b64 s[22:23], 0
	ds_write_b16 v233, v1 offset:53664
.LBB0_810:
	s_andn2_b64 vcc, exec, s[22:23]
	s_cbranch_vccnz .LBB0_814
	v_mov_b32_e32 v1, 0
	s_and_saveexec_b64 s[22:23], s[44:45]
	s_cbranch_execz .LBB0_813
	v_mov_b32_e32 v1, v100
	s_waitcnt lgkmcnt(0)
	v_mul_f32_e32 v1, v6, v1
	v_mul_f32_e64 v1, v1, -v0

; #define LAS __attribute__((address_space(3)))
; __device__ __forceinline__ unsigned pk2(float lo, float hi) { const f32x2_t v = {lo, hi}; const bf16x2_t b = __builtin_convertvector(v, bf16x2_t); return __builtin_bit_cast(unsigned, b); }
; __device__ __forceinline__ void dn_prep_item(const Args& a, LAS unsigned char* lds, int item, int tid, int wave, int lane, int& cwh, int next_item) {
;     ...
;       for (int r = 0; r < 16; ++r) { const int i = 32 * ti + (r & 3) + 8 * (r >> 2) + 4 * hh;
;           const float dec = __expf(fminf(gcs[i] - gj, 0.f));
;           if (isq) { const float v = (i >= j) ? acc[r] * dec : 0.f; *(LAS unsigned short*)(lds + L_AT + i * AS_ + 2 * j) = (unsigned short)(pk2(v, 0.f) & 0xffffu); }
;           else { Lm[i * 68 + j] = (i > j) ? -(betas[i] * acc[r] * dec) : 0.f; } }
.LBB0_814:
	v_mov_b32_e32 v0, v101
	s_and_b64 vcc, exec, s[86:87]
	s_mov_b64 s[22:23], -1
	s_waitcnt lgkmcnt(0)
	v_sub_f32_e32 v0, v0, v16
	v_min_f32_e32 v0, 0, v0
	v_mul_f32_e32 v0, 0x3fb8aa3b, v0
	v_exp_f32_e32 v0, v0
	s_cbranch_vccnz .LBB0_816
	v_mul_f32_e32 v1, v7, v0
	v_cvt_pk_bf16_f32 v1, v1, s0
	v_cndmask_b32_e64 v1, v1, 0, s[46:47]
	s_mov_b64 s[22:23], 0
	ds_write_b16 v233, v1 offset:53808
.LBB0_816:
	s_andn2_b64 vcc, exec, s[22:23]
	s_cbranch_vccnz .LBB0_820
	v_mov_b32_e32 v1, 0
	s_and_saveexec_b64 s[22:23], s[48:49]
	s_cbranch_execz .LBB0_819
	v_mov_b32_e32 v1, v102
	s_waitcnt lgkmcnt(0)
	v_mul_f32_e32 v1, v7, v1
	v_mul_f32_e64 v1, v1, -v0

; #define LAS __attribute__((address_space(3)))
; __device__ __forceinline__ unsigned pk2(float lo, float hi) { const f32x2_t v = {lo, hi}; const bf16x2_t b = __builtin_convertvector(v, bf16x2_t); return __builtin_bit_cast(unsigned, b); }
; __device__ __forceinline__ void dn_prep_item(const Args& a, LAS unsigned char* lds, int item, int tid, int wave, int lane, int& cwh, int next_item) {
;     ...
;       for (int r = 0; r < 16; ++r) { const int i = 32 * ti + (r & 3) + 8 * (r >> 2) + 4 * hh;
;           const float dec = __expf(fminf(gcs[i] - gj, 0.f));
;           if (isq) { const float v = (i >= j) ? acc[r] * dec : 0.f; *(LAS unsigned short*)(lds + L_AT + i * AS_ + 2 * j) = (unsigned short)(pk2(v, 0.f) & 0xffffu); }
;           else { Lm[i * 68 + j] = (i > j) ? -(betas[i] * acc[r] * dec) : 0.f; } }
.LBB0_820:
	v_mov_b32_e32 v0, v103
	s_and_b64 vcc, exec, s[86:87]
	s_mov_b64 s[22:23], -1
	s_waitcnt lgkmcnt(0)
	v_sub_f32_e32 v0, v0, v16
	v_min_f32_e32 v0, 0, v0
	v_mul_f32_e32 v0, 0x3fb8aa3b, v0
	v_exp_f32_e32 v0, v0
	s_cbranch_vccnz .LBB0_822
	v_mul_f32_e32 v1, v8, v0
	v_cvt_pk_bf16_f32 v1, v1, s0
	v_cndmask_b32_e64 v1, v1, 0, s[50:51]
	s_mov_b64 s[22:23], 0
	ds_write_b16 v233, v1 offset:54528
.LBB0_822:
	s_andn2_b64 vcc, exec, s[22:23]
	s_cbranch_vccnz .LBB0_826
	v_mov_b32_e32 v1, 0
	s_and_saveexec_b64 s[22:23], s[52:53]
	s_cbranch_execz .LBB0_825
	v_mov_b32_e32 v1, v104
	s_waitcnt lgkmcnt(0)
	v_mul_f32_e32 v1, v8, v1
	v_mul_f32_e64 v1, v1, -v0

; #define LAS __attribute__((address_space(3)))
; __device__ __forceinline__ unsigned pk2(float lo, float hi) { const f32x2_t v = {lo, hi}; const bf16x2_t b = __builtin_convertvector(v, bf16x2_t); return __builtin_bit_cast(unsigned, b); }
; __device__ __forceinline__ void dn_prep_item(const Args& a, LAS unsigned char* lds, int item, int tid, int wave, int lane, int& cwh, int next_item) {
;     ...
;       for (int r = 0; r < 16; ++r) { const int i = 32 * ti + (r & 3) + 8 * (r >> 2) + 4 * hh;
;           const float dec = __expf(fminf(gcs[i] - gj, 0.f));
;           if (isq) { const float v = (i >= j) ? acc[r] * dec : 0.f; *(LAS unsigned short*)(lds + L_AT + i * AS_ + 2 * j) = (unsigned short)(pk2(v, 0.f) & 0xffffu); }
;           else { Lm[i * 68 + j] = (i > j) ? -(betas[i] * acc[r] * dec) : 0.f; } }
.LBB0_826:
	v_mov_b32_e32 v0, v105
	s_and_b64 vcc, exec, s[86:87]
	s_mov_b64 s[22:23], -1
	s_waitcnt lgkmcnt(0)
	v_sub_f32_e32 v0, v0, v16
	v_min_f32_e32 v0, 0, v0
	v_mul_f32_e32 v0, 0x3fb8aa3b, v0
	v_exp_f32_e32 v0, v0
	s_cbranch_vccnz .LBB0_828
	v_mul_f32_e32 v1, v9, v0
	v_cvt_pk_bf16_f32 v1, v1, s0
	v_cndmask_b32_e64 v1, v1, 0, s[58:59]
	s_mov_b64 s[22:23], 0
	ds_write_b16 v233, v1 offset:54672
.LBB0_828:
	s_andn2_b64 vcc, exec, s[22:23]
	s_cbranch_vccnz .LBB0_832
	v_mov_b32_e32 v1, 0
	s_and_saveexec_b64 s[22:23], s[60:61]
	s_cbranch_execz .LBB0_831
	v_mov_b32_e32 v1, v106
	s_waitcnt lgkmcnt(0)
	v_mul_f32_e32 v1, v9, v1
	v_mul_f32_e64 v1, v1, -v0

; #define LAS __attribute__((address_space(3)))
; __device__ __forceinline__ unsigned pk2(float lo, float hi) { const f32x2_t v = {lo, hi}; const bf16x2_t b = __builtin_convertvector(v, bf16x2_t); return __builtin_bit_cast(unsigned, b); }
; __device__ __forceinline__ void dn_prep_item(const Args& a, LAS unsigned char* lds, int item, int tid, int wave, int lane, int& cwh, int next_item) {
;     ...
;       for (int r = 0; r < 16; ++r) { const int i = 32 * ti + (r & 3) + 8 * (r >> 2) + 4 * hh;
;           const float dec = __expf(fminf(gcs[i] - gj, 0.f));
;           if (isq) { const float v = (i >= j) ? acc[r] * dec : 0.f; *(LAS unsigned short*)(lds + L_AT + i * AS_ + 2 * j) = (unsigned short)(pk2(v, 0.f) & 0xffffu); }
;           else { Lm[i * 68 + j] = (i > j) ? -(betas[i] * acc[r] * dec) : 0.f; } }
.LBB0_832:
	v_mov_b32_e32 v0, v107
	s_and_b64 vcc, exec, s[86:87]
	s_mov_b64 s[22:23], -1
	s_waitcnt lgkmcnt(0)
	v_sub_f32_e32 v0, v0, v16
	v_min_f32_e32 v0, 0, v0
	v_mul_f32_e32 v0, 0x3fb8aa3b, v0
	v_exp_f32_e32 v0, v0
	s_cbranch_vccnz .LBB0_834
	v_mul_f32_e32 v1, v10, v0
	v_cvt_pk_bf16_f32 v1, v1, s0
	v_cndmask_b32_e64 v1, v1, 0, s[62:63]
	s_mov_b64 s[22:23], 0
	ds_write_b16 v233, v1 offset:54816
.LBB0_834:
	s_andn2_b64 vcc, exec, s[22:23]
	s_cbranch_vccnz .LBB0_838
	v_mov_b32_e32 v1, 0
	s_and_saveexec_b64 s[22:23], s[64:65]
	s_cbranch_execz .LBB0_837
	v_mov_b32_e32 v1, v108
	s_waitcnt lgkmcnt(0)
	v_mul_f32_e32 v1, v10, v1
	v_mul_f32_e64 v1, v1, -v0

; #define LAS __attribute__((address_space(3)))
; __device__ __forceinline__ unsigned pk2(float lo, float hi) { const f32x2_t v = {lo, hi}; const bf16x2_t b = __builtin_convertvector(v, bf16x2_t); return __builtin_bit_cast(unsigned, b); }
; __device__ __forceinline__ void dn_prep_item(const Args& a, LAS unsigned char* lds, int item, int tid, int wave, int lane, int& cwh, int next_item) {
;     ...
;       for (int r = 0; r < 16; ++r) { const int i = 32 * ti + (r & 3) + 8 * (r >> 2) + 4 * hh;
;           const float dec = __expf(fminf(gcs[i] - gj, 0.f));
;           if (isq) { const float v = (i >= j) ? acc[r] * dec : 0.f; *(LAS unsigned short*)(lds + L_AT + i * AS_ + 2 * j) = (unsigned short)(pk2(v, 0.f) & 0xffffu); }
;           else { Lm[i * 68 + j] = (i > j) ? -(betas[i] * acc[r] * dec) : 0.f; } }
.LBB0_838:
	v_mov_b32_e32 v0, v109
	s_and_b64 vcc, exec, s[86:87]
	s_mov_b64 s[22:23], -1
	s_waitcnt lgkmcnt(0)
	v_sub_f32_e32 v0, v0, v16
	v_min_f32_e32 v0, 0, v0
	v_mul_f32_e32 v0, 0x3fb8aa3b, v0
	v_exp_f32_e32 v0, v0
	s_cbranch_vccnz .LBB0_840
	v_mul_f32_e32 v1, v11, v0
	v_cvt_pk_bf16_f32 v1, v1, s0
	v_cndmask_b32_e64 v1, v1, 0, s[66:67]
	s_mov_b64 s[22:23], 0
	ds_write_b16 v233, v1 offset:54960
.LBB0_840:
	s_andn2_b64 vcc, exec, s[22:23]
	s_cbranch_vccnz .LBB0_844
	v_mov_b32_e32 v1, 0
	s_and_saveexec_b64 s[22:23], s[68:69]
	s_cbranch_execz .LBB0_843
	v_mov_b32_e32 v1, v110
	s_waitcnt lgkmcnt(0)
	v_mul_f32_e32 v1, v11, v1
	v_mul_f32_e64 v1, v1, -v0

; #define LAS __attribute__((address_space(3)))
; __device__ __forceinline__ unsigned pk2(float lo, float hi) { const f32x2_t v = {lo, hi}; const bf16x2_t b = __builtin_convertvector(v, bf16x2_t); return __builtin_bit_cast(unsigned, b); }
; __device__ __forceinline__ void dn_prep_item(const Args& a, LAS unsigned char* lds, int item, int tid, int wave, int lane, int& cwh, int next_item) {
;     ...
;       for (int r = 0; r < 16; ++r) { const int i = 32 * ti + (r & 3) + 8 * (r >> 2) + 4 * hh;
;           const float dec = __expf(fminf(gcs[i] - gj, 0.f));
;           if (isq) { const float v = (i >= j) ? acc[r] * dec : 0.f; *(LAS unsigned short*)(lds + L_AT + i * AS_ + 2 * j) = (unsigned short)(pk2(v, 0.f) & 0xffffu); }
;           else { Lm[i * 68 + j] = (i > j) ? -(betas[i] * acc[r] * dec) : 0.f; } }
.LBB0_844:
	v_mov_b32_e32 v0, v111
	s_and_b64 vcc, exec, s[86:87]
	s_mov_b64 s[22:23], -1
	s_waitcnt lgkmcnt(0)
	v_sub_f32_e32 v0, v0, v16
	v_min_f32_e32 v0, 0, v0
	v_mul_f32_e32 v0, 0x3fb8aa3b, v0
	v_exp_f32_e32 v0, v0
	s_cbranch_vccnz .LBB0_846
	v_mul_f32_e32 v1, v12, v0
	v_cvt_pk_bf16_f32 v1, v1, s0
	v_cndmask_b32_e64 v1, v1, 0, s[70:71]
	s_mov_b64 s[22:23], 0
	ds_write_b16 v233, v1 offset:55680
.LBB0_846:
	s_andn2_b64 vcc, exec, s[22:23]
	s_cbranch_vccnz .LBB0_850
	v_mov_b32_e32 v1, 0
	s_and_saveexec_b64 s[22:23], s[72:73]
	s_cbranch_execz .LBB0_849
	v_mov_b32_e32 v1, v112
	s_waitcnt lgkmcnt(0)
	v_mul_f32_e32 v1, v12, v1
	v_mul_f32_e64 v1, v1, -v0

; #define LAS __attribute__((address_space(3)))
; __device__ __forceinline__ unsigned pk2(float lo, float hi) { const f32x2_t v = {lo, hi}; const bf16x2_t b = __builtin_convertvector(v, bf16x2_t); return __builtin_bit_cast(unsigned, b); }
; __device__ __forceinline__ void dn_prep_item(const Args& a, LAS unsigned char* lds, int item, int tid, int wave, int lane, int& cwh, int next_item) {
;     ...
;       for (int r = 0; r < 16; ++r) { const int i = 32 * ti + (r & 3) + 8 * (r >> 2) + 4 * hh;
;           const float dec = __expf(fminf(gcs[i] - gj, 0.f));
;           if (isq) { const float v = (i >= j) ? acc[r] * dec : 0.f; *(LAS unsigned short*)(lds + L_AT + i * AS_ + 2 * j) = (unsigned short)(pk2(v, 0.f) & 0xffffu); }
;           else { Lm[i * 68 + j] = (i > j) ? -(betas[i] * acc[r] * dec) : 0.f; } }
.LBB0_850:
	v_mov_b32_e32 v0, v113
	s_and_b64 vcc, exec, s[86:87]
	s_mov_b64 s[22:23], -1
	s_waitcnt lgkmcnt(0)
	v_sub_f32_e32 v0, v0, v16
	v_min_f32_e32 v0, 0, v0
	v_mul_f32_e32 v0, 0x3fb8aa3b, v0
	v_exp_f32_e32 v0, v0
	s_cbranch_vccnz .LBB0_852
	v_mul_f32_e32 v1, v13, v0
	v_cvt_pk_bf16_f32 v1, v1, s0
	v_cndmask_b32_e64 v1, v1, 0, s[74:75]
	s_mov_b64 s[22:23], 0
	ds_write_b16 v233, v1 offset:55824
.LBB0_852:
	s_andn2_b64 vcc, exec, s[22:23]
	s_cbranch_vccnz .LBB0_856
	v_mov_b32_e32 v1, 0
	s_and_saveexec_b64 s[22:23], s[76:77]
	s_cbranch_execz .LBB0_855
	v_mov_b32_e32 v1, v114
	s_waitcnt lgkmcnt(0)
	v_mul_f32_e32 v1, v13, v1
	v_mul_f32_e64 v1, v1, -v0

; #define LAS __attribute__((address_space(3)))
; __device__ __forceinline__ unsigned pk2(float lo, float hi) { const f32x2_t v = {lo, hi}; const bf16x2_t b = __builtin_convertvector(v, bf16x2_t); return __builtin_bit_cast(unsigned, b); }
; __device__ __forceinline__ void dn_prep_item(const Args& a, LAS unsigned char* lds, int item, int tid, int wave, int lane, int& cwh, int next_item) {
;     ...
;       for (int r = 0; r < 16; ++r) { const int i = 32 * ti + (r & 3) + 8 * (r >> 2) + 4 * hh;
;           const float dec = __expf(fminf(gcs[i] - gj, 0.f));
;           if (isq) { const float v = (i >= j) ? acc[r] * dec : 0.f; *(LAS unsigned short*)(lds + L_AT + i * AS_ + 2 * j) = (unsigned short)(pk2(v, 0.f) & 0xffffu); }
;           else { Lm[i * 68 + j] = (i > j) ? -(betas[i] * acc[r] * dec) : 0.f; } }
.LBB0_856:
	v_mov_b32_e32 v0, v115
	s_and_b64 vcc, exec, s[86:87]
	s_mov_b64 s[22:23], -1
	s_waitcnt lgkmcnt(0)
	v_sub_f32_e32 v0, v0, v16
	v_min_f32_e32 v0, 0, v0
	v_mul_f32_e32 v0, 0x3fb8aa3b, v0
	v_exp_f32_e32 v0, v0
	s_cbranch_vccnz .LBB0_858
	v_mul_f32_e32 v1, v14, v0
	v_cvt_pk_bf16_f32 v1, v1, s0
	v_cndmask_b32_e64 v1, v1, 0, s[78:79]
	s_mov_b64 s[22:23], 0
	ds_write_b16 v233, v1 offset:55968
.LBB0_858:
	s_andn2_b64 vcc, exec, s[22:23]
	s_cbranch_vccnz .LBB0_862
	v_mov_b32_e32 v1, 0
	s_and_saveexec_b64 s[22:23], s[80:81]
	s_cbranch_execz .LBB0_861
	v_mov_b32_e32 v1, v116
	s_waitcnt lgkmcnt(0)
	v_mul_f32_e32 v1, v14, v1
	v_mul_f32_e64 v1, v1, -v0

; #define LAS __attribute__((address_space(3)))
; __device__ __forceinline__ unsigned pk2(float lo, float hi) { const f32x2_t v = {lo, hi}; const bf16x2_t b = __builtin_convertvector(v, bf16x2_t); return __builtin_bit_cast(unsigned, b); }
; __device__ __forceinline__ void dn_prep_item(const Args& a, LAS unsigned char* lds, int item, int tid, int wave, int lane, int& cwh, int next_item) {
;     ...
;       for (int r = 0; r < 16; ++r) { const int i = 32 * ti + (r & 3) + 8 * (r >> 2) + 4 * hh;
;           const float dec = __expf(fminf(gcs[i] - gj, 0.f));
;           if (isq) { const float v = (i >= j) ? acc[r] * dec : 0.f; *(LAS unsigned short*)(lds + L_AT + i * AS_ + 2 * j) = (unsigned short)(pk2(v, 0.f) & 0xffffu); }
;           else { Lm[i * 68 + j] = (i > j) ? -(betas[i] * acc[r] * dec) : 0.f; } }
.LBB0_862:
	v_mov_b32_e32 v0, v117
	s_and_b64 vcc, exec, s[86:87]
	s_mov_b64 s[22:23], -1
	s_waitcnt lgkmcnt(0)
	v_sub_f32_e32 v0, v0, v16
	v_min_f32_e32 v0, 0, v0
	v_mul_f32_e32 v0, 0x3fb8aa3b, v0
	v_exp_f32_e32 v0, v0
	s_cbranch_vccnz .LBB0_864
	v_mul_f32_e32 v1, v15, v0
	v_cvt_pk_bf16_f32 v1, v1, s0
	v_cndmask_b32_e64 v1, v1, 0, s[82:83]
	s_mov_b64 s[22:23], 0
	ds_write_b16 v233, v1 offset:56112
.LBB0_864:
	s_andn2_b64 vcc, exec, s[22:23]
	s_cbranch_vccnz .LBB0_868
	v_mov_b32_e32 v1, 0
	s_and_saveexec_b64 s[22:23], s[84:85]
	s_cbranch_execz .LBB0_867
	v_mov_b32_e32 v1, v118
	s_waitcnt lgkmcnt(0)
	v_mul_f32_e32 v1, v15, v1
	v_mul_f32_e64 v1, v1, -v0
